# P2 diagonal tile also evaluated as products of sigmoids with the strict-causal lane masks; V2/V3 loads issued right after the QK MFMAs
# baseline (speedup 1.0000x reference)
; template <bool DIAG>
; __device__ __forceinline__ void sb_tile(const bf16x8 (&kf)[4], const bf16x8 (&vf)[4], const bf16x8 (&qf)[4], f32x16& o0, f32x16& o1, float& c, int rel0, int hi) {
;     f32x16 s;
; #pragma unroll
;     for (int r = 0; r < 16; ++r) s[r] = 0.f;
; #pragma unroll
;     for (int d0 = 0; d0 < 4; ++d0) s = __builtin_amdgcn_mfma_f32_32x32x16_bf16(kf[d0], qf[d0], s, 0, 0, 0);
;     float L[16]; float tot = 0.f;
; #pragma unroll
;     for (int r = 15; r >= 0; --r) {
;         const float z = s[r];
;         const float sp = fmaxf(z, 0.f) + __builtin_amdgcn_logf(1.0f + __builtin_amdgcn_exp2f(-fabsf(z)));
;         if (DIAG) tot += (r < rel0) ? -sp : 0.f; else tot -= sp;
;         L[r] = tot;
;     }
;     const float tot_o = __shfl_xor(tot, 32);
;     const float add = c + (hi == 0 ? tot_o : 0.f);
;     float w[16];
; #pragma unroll
;     for (int r = 0; r < 16; ++r) {
;         const float e = __builtin_amdgcn_exp2f(s[r] + L[r] + add);
;         w[r] = DIAG ? ((r < rel0) ? e : 0.f) : e;
;     }
;     c += tot + tot_o;
;     u32x4 p0, p1;
;     p0.x = cvt_pk_bf16(w[0], w[1]); p0.y = cvt_pk_bf16(w[2], w[3]); p0.z = cvt_pk_bf16(w[4], w[5]); p0.w = cvt_pk_bf16(w[6], w[7]);
;     p1.x = cvt_pk_bf16(w[8], w[9]); p1.y = cvt_pk_bf16(w[10], w[11]); p1.z = cvt_pk_bf16(w[12], w[13]); p1.w = cvt_pk_bf16(w[14], w[15]);
;     const bf16x8 pf0 = __builtin_bit_cast(bf16x8, p0), pf1 = __builtin_bit_cast(bf16x8, p1);
;     o0 = __builtin_amdgcn_mfma_f32_32x32x16_bf16(vf[0], pf0, o0, 0, 0, 0);
;     o0 = __builtin_amdgcn_mfma_f32_32x32x16_bf16(vf[1], pf1, o0, 0, 0, 0);
;     o1 = __builtin_amdgcn_mfma_f32_32x32x16_bf16(vf[2], pf0, o1, 0, 0, 0);
;     o1 = __builtin_amdgcn_mfma_f32_32x32x16_bf16(vf[3], pf1, o1, 0, 0, 0);
; }
; __device__ __forceinline__ void sb_attn_unit(const bf16_t* __restrict__ Q, const bf16_t* __restrict__ Kb, const bf16_t* __restrict__ VT, bf16_t* __restrict__ MIX, int b, int h, int qb, int lane) {
;     ...
;     for (int i = 0; i < 4; ++i) { kf[i] = *(const bf16x8*)(kp + (size_t)q0 * 64 + 512 * i); vf[i] = *(const bf16x8*)(vp + (size_t)q0 * 64 + 512 * i); }
;     int kvn = q0 >= 32 ? q0 - 32 : 0;
; #pragma unroll
;     for (int i = 0; i < 4; ++i) { kn[i] = *(const bf16x8*)(kp + (size_t)kvn * 64 + 512 * i); vn[i] = *(const bf16x8*)(vp + (size_t)kvn * 64 + 512 * i); }
;     sb_tile<true>(kf, vf, qf, o0, o1, c, q - 16 * hi, hi);
.LBB0_353:
	s_ashr_i32 s52, s3, 11
	s_bfe_u32 s60, s3, 0x30008
	s_lshl_b32 s50, s52, 3
	s_or_b32 s54, s50, s60
	s_ashr_i32 s55, s54, 31
	s_and_b32 s53, s3, 0xff
	s_lshl_b64 s[56:57], s[54:55], 13
	s_lshl_b64 s[54:55], s[54:55], 20
	v_lshl_add_u64 v[86:87], v[82:83], 0, s[54:55]
	s_lshl_b32 s50, s53, 12
	v_lshl_add_u64 v[24:25], v[86:87], 0, s[50:51]
	global_load_dwordx4 v[0:3], v[24:25], off
	s_lshl_b32 s61, s53, 5
	s_or_b32 s56, s56, s61
	v_mov_b32_e32 v5, s57
	v_or_b32_e32 v4, s56, v76
	v_lshlrev_b64 v[4:5], 7, v[4:5]
	v_lshl_add_u64 v[30:31], v[80:81], 0, v[4:5]
	global_load_dwordx4 v[48:51], v[30:31], off
	global_load_dwordx4 v[16:19], v[24:25], off offset:1024
	global_load_dwordx4 v[52:55], v[30:31], off offset:32
	global_load_dwordx4 v[20:23], v[24:25], off offset:2048
	global_load_dwordx4 v[56:59], v[30:31], off offset:64
	global_load_dwordx4 v[26:29], v[24:25], off offset:3072
	global_load_dwordx4 v[60:63], v[30:31], off offset:96
	v_lshl_add_u64 v[88:89], v[84:85], 0, s[54:55]
	v_lshl_add_u64 v[24:25], v[88:89], 0, s[50:51]
	s_sub_i32 s50, s61, 32
	s_cmp_lg_u32 s53, 0
	s_cselect_b32 s54, s50, 0
	s_waitcnt vmcnt(0)
	v_mfma_f32_32x32x16_bf16 v[0:15], v[0:3], v[48:51], 0
	v_mfma_f32_32x32x16_bf16 v[0:15], v[16:19], v[52:55], v[0:15]
	v_mfma_f32_32x32x16_bf16 v[0:15], v[20:23], v[56:59], v[0:15]
	global_load_dwordx4 v[20:23], v[24:25], off
	global_load_dwordx4 v[16:19], v[24:25], off offset:1024
	v_mfma_f32_32x32x16_bf16 v[0:15], v[26:29], v[60:63], v[0:15]
	global_load_dwordx4 v[26:29], v[24:25], off offset:2048
	global_load_dwordx4 v[38:41], v[24:25], off offset:3072
	s_nop 9
	v_exp_f32_e32 v15, v15
	v_exp_f32_e32 v14, v14
	v_exp_f32_e32 v13, v13
	v_exp_f32_e32 v12, v12
	v_exp_f32_e32 v11, v11
	v_exp_f32_e32 v10, v10
	v_exp_f32_e32 v9, v9
	v_exp_f32_e32 v8, v8
	v_exp_f32_e32 v7, v7
	v_exp_f32_e32 v6, v6
	v_exp_f32_e32 v5, v5
	v_exp_f32_e32 v4, v4
	v_exp_f32_e32 v3, v3
	v_exp_f32_e32 v2, v2
	v_exp_f32_e32 v1, v1
	v_exp_f32_e32 v0, v0
	v_add_f32_e32 v113, 1.0, v15
	v_add_f32_e32 v112, 1.0, v14
	v_add_f32_e32 v111, 1.0, v13
	v_add_f32_e32 v110, 1.0, v12
	v_add_f32_e32 v109, 1.0, v11
	v_add_f32_e32 v108, 1.0, v10
	v_add_f32_e32 v107, 1.0, v9
	v_add_f32_e32 v106, 1.0, v8
	v_add_f32_e32 v105, 1.0, v7
	v_add_f32_e32 v104, 1.0, v6
	v_add_f32_e32 v103, 1.0, v5
	v_add_f32_e32 v102, 1.0, v4
	v_add_f32_e32 v101, 1.0, v3
	v_add_f32_e32 v100, 1.0, v2
	v_add_f32_e32 v99, 1.0, v1
	v_add_f32_e32 v98, 1.0, v0
	v_rcp_f32_e32 v113, v113
	v_rcp_f32_e32 v112, v112
	v_rcp_f32_e32 v111, v111
	v_rcp_f32_e32 v110, v110
	v_rcp_f32_e32 v109, v109
	v_rcp_f32_e32 v108, v108
	v_rcp_f32_e32 v107, v107
	v_rcp_f32_e32 v106, v106
	v_rcp_f32_e32 v105, v105
	v_rcp_f32_e32 v104, v104
	v_rcp_f32_e32 v103, v103
	v_rcp_f32_e32 v102, v102
	v_rcp_f32_e32 v101, v101
	v_rcp_f32_e32 v100, v100
	v_rcp_f32_e32 v99, v99
	v_rcp_f32_e32 v98, v98
	v_cndmask_b32_e64 v113, 1.0, v113, s[6:7]
	v_cndmask_b32_e64 v112, 1.0, v112, s[8:9]
	v_cndmask_b32_e64 v111, 1.0, v111, s[10:11]
	v_cndmask_b32_e64 v110, 1.0, v110, s[12:13]
	v_cndmask_b32_e64 v109, 1.0, v109, s[14:15]
	v_cndmask_b32_e64 v108, 1.0, v108, s[16:17]
	v_cndmask_b32_e64 v107, 1.0, v107, s[18:19]
	v_cndmask_b32_e64 v106, 1.0, v106, s[20:21]
	v_cndmask_b32_e64 v105, 1.0, v105, s[22:23]
	v_cndmask_b32_e64 v104, 1.0, v104, s[24:25]
	v_cndmask_b32_e64 v103, 1.0, v103, s[26:27]
	v_cndmask_b32_e64 v102, 1.0, v102, s[28:29]
	v_cndmask_b32_e64 v101, 1.0, v101, s[30:31]
	v_cndmask_b32_e64 v100, 1.0, v100, s[34:35]
	v_cndmask_b32_e64 v99, 1.0, v99, s[36:37]
	v_cndmask_b32_e64 v98, 1.0, v98, s[38:39]
	v_mul_f32_e32 v112, v112, v113
	v_mul_f32_e32 v111, v111, v112
	v_mul_f32_e32 v110, v110, v111
	v_mul_f32_e32 v109, v109, v110
	v_mul_f32_e32 v108, v108, v109
	v_mul_f32_e32 v107, v107, v108
	v_mul_f32_e32 v106, v106, v107
	v_mul_f32_e32 v105, v105, v106
	v_mul_f32_e32 v104, v104, v105
	v_mul_f32_e32 v103, v103, v104
	v_mul_f32_e32 v102, v102, v103
	v_mul_f32_e32 v101, v101, v102
	v_mul_f32_e32 v100, v100, v101
	v_mul_f32_e32 v99, v99, v100
	v_mul_f32_e32 v98, v98, v99
	ds_bpermute_b32 v115, v77, v98
	v_mul_f32_e32 v15, v15, v113
	v_mul_f32_e32 v14, v14, v112
	v_mul_f32_e32 v13, v13, v111
	v_mul_f32_e32 v12, v12, v110
	v_mul_f32_e32 v11, v11, v109
	v_mul_f32_e32 v10, v10, v108
	v_mul_f32_e32 v9, v9, v107
	v_mul_f32_e32 v8, v8, v106
	v_mul_f32_e32 v7, v7, v105
	v_mul_f32_e32 v6, v6, v104
	v_mul_f32_e32 v5, v5, v103
	v_mul_f32_e32 v4, v4, v102
	v_mul_f32_e32 v3, v3, v101
	v_mul_f32_e32 v2, v2, v100
	v_mul_f32_e32 v1, v1, v99
	v_mul_f32_e32 v0, v0, v98
	s_waitcnt lgkmcnt(0)
	v_cndmask_b32_e64 v114, 1.0, v115, s[40:41]
	v_mul_f32_e32 v0, v0, v114
	v_mul_f32_e32 v1, v1, v114
	v_mul_f32_e32 v2, v2, v114
	v_mul_f32_e32 v3, v3, v114
	v_mul_f32_e32 v4, v4, v114
	v_mul_f32_e32 v5, v5, v114
	v_mul_f32_e32 v6, v6, v114
	v_mul_f32_e32 v7, v7, v114
	v_mul_f32_e32 v8, v8, v114
	v_mul_f32_e32 v9, v9, v114
	v_mul_f32_e32 v10, v10, v114
	v_mul_f32_e32 v11, v11, v114
	v_mul_f32_e32 v12, v12, v114
	v_mul_f32_e32 v13, v13, v114
	v_mul_f32_e32 v14, v14, v114
	v_mul_f32_e32 v15, v15, v114
	v_cndmask_b32_e64 v0, 0, v0, s[38:39]
	v_cndmask_b32_e64 v1, 0, v1, s[36:37]
	v_cndmask_b32_e64 v2, 0, v2, s[34:35]
	v_cndmask_b32_e64 v3, 0, v3, s[30:31]
	v_cndmask_b32_e64 v4, 0, v4, s[28:29]
	v_cndmask_b32_e64 v5, 0, v5, s[26:27]
	v_cndmask_b32_e64 v6, 0, v6, s[24:25]
	v_cndmask_b32_e64 v7, 0, v7, s[22:23]
	v_cndmask_b32_e64 v8, 0, v8, s[20:21]
	v_cndmask_b32_e64 v9, 0, v9, s[18:19]
	v_cndmask_b32_e64 v10, 0, v10, s[16:17]
	v_cndmask_b32_e64 v11, 0, v11, s[14:15]
	v_cndmask_b32_e64 v12, 0, v12, s[12:13]
	v_cndmask_b32_e64 v13, 0, v13, s[10:11]
	v_cndmask_b32_e64 v14, 0, v14, s[8:9]
	v_cndmask_b32_e64 v15, 0, v15, s[6:7]
	v_cvt_pk_bf16_f32 v30, v0, v1
	v_cvt_pk_bf16_f32 v31, v2, v3
	v_cvt_pk_bf16_f32 v32, v4, v5
	v_cvt_pk_bf16_f32 v33, v6, v7
	v_cvt_pk_bf16_f32 v34, v8, v9
	v_cvt_pk_bf16_f32 v35, v10, v11
	v_cvt_pk_bf16_f32 v36, v12, v13
	v_cvt_pk_bf16_f32 v37, v14, v15
	v_mul_f32_e32 v120, v98, v115
	v_log_f32_e32 v120, v120
	s_waitcnt vmcnt(0)
	v_mfma_f32_32x32x16_bf16 v[0:15], v[20:23], v[30:33], 0
	v_mfma_f32_32x32x16_bf16 v[0:15], v[16:19], v[34:37], v[0:15]
	v_mfma_f32_32x32x16_bf16 v[16:31], v[26:29], v[30:33], 0
	v_add_f32_e32 v90, 0, v120
	v_mfma_f32_32x32x16_bf16 v[16:31], v[38:41], v[34:37], v[16:31]
	s_branch .LBB0_355
